# sgemm MODE1 tile loads pipelined (global_load + counted vmcnt)
# baseline (speedup 1.0000x reference)
; #define LAS __attribute__((address_space(3)))
; template <int MODE>
; __device__ __forceinline__ void sgemm_phase(LAS unsigned char* lds, const SgArgs g, int ntiles, int bid, int G) {
;     ...
;     for (int t = bid; t < ntiles; t += G) {
;         const int ct = t >> 3, rt = t & 7;
;         const int brow0 = MODE == 0 ? 256 * (ct >> 2) + 32 * (ct & 3) : 64 * ct, brow1 = MODE == 0 ? brow0 + 128 : brow0 + 32;
;         const bf16_t* ap = g.A + (size_t)(MP + rt * 32 + r32) * g.lda + wave * kw + hi * 8;
;         const bf16_t* bp0 = g.Bt + (size_t)(brow0 + r32) * g.ldb + wave * kw + hi * 8;
;         const bf16_t* bp1 = g.Bt + (size_t)(brow1 + r32) * g.ldb + wave * kw + hi * 8;
;         f32x16 c0 = {}, c1 = {};
;         for (int k0 = 0; k0 < kw; k0 += 128) {
;             bf16x8 a[8], b0[8], b1[8];
; #pragma unroll
;             for (int i = 0; i < 8; ++i) if (k0 + 16 * i < kw) { a[i] = *(const bf16x8*)(ap + k0 + 16 * i); b0[i] = *(const bf16x8*)(bp0 + k0 + 16 * i); b1[i] = *(const bf16x8*)(bp1 + k0 + 16 * i); }
;             asm volatile("" ::: "memory");
; #pragma unroll
;             for (int i = 0; i < 8; ++i) if (k0 + 16 * i < kw) { c0 = __builtin_amdgcn_mfma_f32_32x32x16_bf16(a[i], b0[i], c0, 0, 0, 0); c1 = __builtin_amdgcn_mfma_f32_32x32x16_bf16(a[i], b1[i], c1, 0, 0, 0); }
;         }
;         LAS float* red = (LAS float*)lds + wave * 2048;
; #pragma unroll
;         for (int r = 0; r < 16; ++r) { const int row = (r & 3) + 8 * (r >> 2) + 4 * hi; red[row * 64 + r32] = c0[r]; red[row * 64 + 32 + r32] = c1[r]; }
;         __syncthreads();
.LBB0_586:
	s_and_b32 s1, s5, 0xe0
	s_and_b32 s0, s4, 0xffffffc0
	s_bitset1_b32 s1, 15
	v_or_b32_e32 v2, s0, v40
	v_or_b32_e32 v0, s1, v40
	v_ashrrev_i32_e32 v3, 31, v2
	v_or_b32_e32 v4, 32, v2
	v_lshlrev_b32_e32 v0, 11, v0
	v_lshlrev_b64 v[2:3], 11, v[2:3]
	v_ashrrev_i32_e32 v5, 31, v4
	v_lshl_add_u64 v[56:57], v[34:35], 0, v[0:1]
	v_lshl_add_u64 v[58:59], v[36:37], 0, v[2:3]
	v_lshlrev_b64 v[6:7], 11, v[4:5]
	v_lshl_add_u64 v[60:61], v[36:37], 0, v[6:7]
	global_load_dwordx4 v[190:193], v[56:57], off
	global_load_dwordx4 v[222:225], v[58:59], off
	global_load_dwordx4 v[132:135], v[60:61], off
	global_load_dwordx4 v[194:197], v[56:57], off offset:32
	global_load_dwordx4 v[226:229], v[58:59], off offset:32
	global_load_dwordx4 v[136:139], v[60:61], off offset:32
	global_load_dwordx4 v[198:201], v[56:57], off offset:64
	global_load_dwordx4 v[230:233], v[58:59], off offset:64
	global_load_dwordx4 v[140:143], v[60:61], off offset:64
	global_load_dwordx4 v[202:205], v[56:57], off offset:96
	global_load_dwordx4 v[234:237], v[58:59], off offset:96
	global_load_dwordx4 v[144:147], v[60:61], off offset:96
	global_load_dwordx4 v[206:209], v[56:57], off offset:128
	global_load_dwordx4 v[238:241], v[58:59], off offset:128
	global_load_dwordx4 v[148:151], v[60:61], off offset:128
	global_load_dwordx4 v[210:213], v[56:57], off offset:160
	global_load_dwordx4 v[242:245], v[58:59], off offset:160
	global_load_dwordx4 v[152:155], v[60:61], off offset:160
	global_load_dwordx4 v[214:217], v[56:57], off offset:192
	global_load_dwordx4 v[246:249], v[58:59], off offset:192
	global_load_dwordx4 v[156:159], v[60:61], off offset:192
	global_load_dwordx4 v[218:221], v[56:57], off offset:224
	global_load_dwordx4 v[250:253], v[58:59], off offset:224
	global_load_dwordx4 v[164:167], v[60:61], off offset:224
	v_add_u32_e32 v0, 0x800, v41
	v_add_u32_e32 v39, 0x1000, v41
	s_add_i32 s6, s6, s3
	s_add_i32 s5, s5, s7
	s_add_i32 s4, s4, s8
	v_add_u32_e32 v56, 0x1800, v41
	v_add_u32_e32 v57, 0x2000, v43
	v_add_u32_e32 v52, s1, v42
	v_ashrrev_i32_e32 v53, 31, v52
	v_lshlrev_b64 v[54:55], 6, v[52:53]
	v_lshl_add_u64 v[54:55], s[12:13], 0, v[54:55]
	s_ashr_i32 s1, s0, 31
	s_cmpk_lt_i32 s6, 0x100
	s_waitcnt vmcnt(21)
	v_mfma_f32_32x32x16_bf16 v[2:17], v[190:193], v[222:225], 0
	v_mfma_f32_32x32x16_bf16 v[18:33], v[190:193], v[132:135], 0
	s_waitcnt vmcnt(18)
	v_mfma_f32_32x32x16_bf16 v[2:17], v[194:197], v[226:229], v[2:17]
	v_mfma_f32_32x32x16_bf16 v[18:33], v[194:197], v[136:139], v[18:33]
	s_waitcnt vmcnt(15)
	v_mfma_f32_32x32x16_bf16 v[2:17], v[198:201], v[230:233], v[2:17]
	v_mfma_f32_32x32x16_bf16 v[18:33], v[198:201], v[140:143], v[18:33]
	s_waitcnt vmcnt(12)
	v_mfma_f32_32x32x16_bf16 v[2:17], v[202:205], v[234:237], v[2:17]
	v_mfma_f32_32x32x16_bf16 v[18:33], v[202:205], v[144:147], v[18:33]
	s_waitcnt vmcnt(9)
	v_mfma_f32_32x32x16_bf16 v[2:17], v[206:209], v[238:241], v[2:17]
	v_mfma_f32_32x32x16_bf16 v[18:33], v[206:209], v[148:151], v[18:33]
	s_waitcnt vmcnt(6)
	v_mfma_f32_32x32x16_bf16 v[2:17], v[210:213], v[242:245], v[2:17]
	v_mfma_f32_32x32x16_bf16 v[18:33], v[210:213], v[152:155], v[18:33]
	s_waitcnt vmcnt(3)
	v_mfma_f32_32x32x16_bf16 v[2:17], v[214:217], v[246:249], v[2:17]
	v_mfma_f32_32x32x16_bf16 v[18:33], v[214:217], v[156:159], v[18:33]
	s_waitcnt vmcnt(0)
	v_mfma_f32_32x32x16_bf16 v[2:17], v[218:221], v[250:253], v[2:17]
	v_mfma_f32_32x32x16_bf16 v[18:33], v[218:221], v[164:167], v[18:33]
	s_nop 11
	ds_write2_b32 v41, v2, v18 offset1:32
	ds_write2_b32 v41, v3, v19 offset0:64 offset1:96
	ds_write2_b32 v41, v4, v20 offset0:128 offset1:160
	ds_write2_b32 v41, v5, v21 offset0:192 offset1:224
	ds_write2_b32 v0, v6, v22 offset1:32
	ds_write2_b32 v0, v7, v23 offset0:64 offset1:96
	ds_write2_b32 v0, v8, v24 offset0:128 offset1:160
	ds_write2_b32 v0, v9, v25 offset0:192 offset1:224
	ds_write2_b32 v39, v10, v26 offset1:32
	ds_write2_b32 v39, v11, v27 offset0:64 offset1:96
	ds_write2_b32 v39, v12, v28 offset0:128 offset1:160
	ds_write2_b32 v39, v13, v29 offset0:192 offset1:224
	ds_write2_b32 v56, v14, v30 offset1:32
	ds_write2_b32 v56, v15, v31 offset0:64 offset1:96
	ds_write2_b32 v56, v16, v32 offset0:128 offset1:160
	ds_write2_b32 v56, v17, v33 offset0:192 offset1:224
	s_waitcnt lgkmcnt(0)
	s_barrier
; #define LAS __attribute__((address_space(3)))
; __device__ __forceinline__ unsigned cvt_pk_bf16(float lo, float hi) { unsigned r; asm volatile("v_cvt_pk_bf16_f32 %0, %1, %2" : "=v"(r) : "v"(lo), "v"(hi)); return r; }
; __device__ __forceinline__ float row_rstd(const float* ssq, int row) {
;     const f32x4* p = (const f32x4*)(ssq + (size_t)row * 16);
;     const f32x4 a = p[0], b = p[1], c = p[2], d = p[3];
;     const float s = (((a.x + a.y) + (a.z + a.w)) + ((b.x + b.y) + (b.z + b.w))) + (((c.x + c.y) + (c.z + c.w)) + ((d.x + d.y) + (d.z + d.w)));
;     return rsqrtf(s * (1.0f / 1024.0f) + EPS);
; template <int MODE>
; __device__ __forceinline__ void sgemm_phase(LAS unsigned char* lds, const SgArgs g, int ntiles, int bid, int G) {
;     ...
;         const int row = tid >> 4, q = tid & 15; float v0 = 0.f, v1 = 0.f, v2 = 0.f, v3 = 0.f;
; #pragma unroll
;         for (int w = 0; w < 8; ++w) { const LAS float* p = (const LAS float*)lds + w * 2048 + row * 64 + 2 * q; const f32x2 lo = *(const LAS f32x2*)p, hi2 = *(const LAS f32x2*)(p + 32); v0 += lo.x; v1 += lo.y; v2 += hi2.x; v3 += hi2.y; }
;         const int grow = MP + rt * 32 + row;
;         if (MODE == 0) {
;             const float rs = row_rstd(g.ssq_in, grow); const float g0 = v0 * rs, g1 = v1 * rs, u0 = v2 * rs, u1 = v3 * rs;
;             const float a0 = g0 * __builtin_amdgcn_rcpf(1.0f + __builtin_amdgcn_exp2f(-1.4426950408889634f * g0)) * u0, a1 = g1 * __builtin_amdgcn_rcpf(1.0f + __builtin_amdgcn_exp2f(-1.4426950408889634f * g1)) * u1;
;             *(unsigned*)(g.O + (size_t)grow * g.ldc + 128 * (ct >> 2) + 32 * (ct & 3) + 2 * q) = cvt_pk_bf16(a0, a1);
;         } else if (MODE == 1) {
;             const float rs = row_rstd(g.ssq_in, grow); bf16_t* op = g.O + (size_t)grow * g.ldc + 64 * ct + 2 * q;
;             *(unsigned*)op = cvt_pk_bf16(v0 * rs, v1 * rs); *(unsigned*)(op + 32) = cvt_pk_bf16(v2 * rs, v3 * rs);
	flat_load_dwordx4 v[2:5], v[54:55]
	flat_load_dwordx4 v[6:9], v[54:55] offset:32
	flat_load_dwordx4 v[10:13], v[54:55] offset:16
	flat_load_dwordx4 v[14:17], v[54:55] offset:48
	v_lshlrev_b64 v[18:19], 12, v[52:53]
	v_lshl_add_u64 v[18:19], s[16:17], 0, v[18:19]
	v_add_u32_e32 v30, 0x6000, v43
	v_add_u32_e32 v44, 0x8000, v43
	v_add_u32_e32 v48, 0xa000, v43
	v_add_u32_e32 v54, 0xc000, v43
	v_add_u32_e32 v56, 0xe000, v43
	v_mov_b32_e32 v39, v1
	v_lshl_add_u64 v[18:19], s[0:1], 1, v[18:19]
	v_add_u32_e32 v0, 0x4000, v43
	v_lshl_add_u64 v[60:61], v[18:19], 0, v[38:39]
	ds_read2_b64 v[18:21], v43 offset1:16
	ds_read2_b64 v[22:25], v57 offset1:16
	ds_read2_b64 v[26:29], v0 offset1:16
	ds_read2_b64 v[30:33], v30 offset1:16
	ds_read2_b64 v[44:47], v44 offset1:16
	ds_read2_b64 v[48:51], v48 offset1:16
	ds_read2_b64 v[52:55], v54 offset1:16
	ds_read2_b64 v[56:59], v56 offset1:16
	s_waitcnt lgkmcnt(0)
	v_add_f32_e32 v0, 0, v18
	v_add_f32_e32 v18, 0, v19
	v_add_f32_e32 v19, 0, v20
	v_add_f32_e32 v18, v18, v23
	v_add_f32_e32 v19, v19, v24
	v_add_f32_e32 v18, v18, v27
	v_add_f32_e32 v19, v19, v28
	v_add_f32_e32 v18, v18, v31
	v_add_f32_e32 v19, v19, v32
	v_add_f32_e32 v18, v18, v45
	v_add_f32_e32 v19, v19, v46
	v_add_f32_e32 v18, v18, v49
	v_add_f32_e32 v19, v19, v50
	v_add_f32_e32 v18, v18, v53
	v_add_f32_e32 v19, v19, v54
	v_add_f32_e32 v20, 0, v21
	v_add_f32_e32 v0, v0, v22
	v_add_f32_e32 v21, v18, v57
	v_add_f32_e32 v22, v19, v58
	v_add_f32_e32 v0, v0, v26
	v_add_f32_e32 v20, v20, v25
	v_add_f32_e32 v0, v0, v30
	v_add_f32_e32 v20, v20, v29
	v_add_f32_e32 v0, v0, v44
	v_add_f32_e32 v20, v20, v33
	v_add_f32_e32 v0, v0, v48
	v_add_f32_e32 v20, v20, v47
	v_add_f32_e32 v0, v0, v52
	v_add_f32_e32 v20, v20, v51
	v_add_f32_e32 v0, v0, v56
	v_add_f32_e32 v20, v20, v55
	v_add_f32_e32 v20, v20, v59
	s_waitcnt vmcnt(0)
	v_mov_b32_e32 v18, v2
	v_mov_b32_e32 v19, v6
	v_mov_b32_e32 v6, v3
	v_mov_b32_e32 v2, v4
	v_mov_b32_e32 v3, v8
	v_mov_b32_e32 v8, v5
	v_mov_b32_e32 v4, v10
	v_mov_b32_e32 v5, v14
	v_mov_b32_e32 v14, v11
	v_mov_b32_e32 v10, v12
	v_mov_b32_e32 v11, v16
	v_mov_b32_e32 v16, v13
	v_pk_add_f32 v[6:7], v[18:19], v[6:7]
	v_pk_add_f32 v[2:3], v[2:3], v[8:9]
	v_pk_add_f32 v[4:5], v[4:5], v[14:15]
	v_pk_add_f32 v[8:9], v[10:11], v[16:17]
	v_pk_add_f32 v[2:3], v[6:7], v[2:3]
	v_pk_add_f32 v[4:5], v[4:5], v[8:9]
	s_nop 0
	v_pk_add_f32 v[2:3], v[2:3], v[4:5]
	s_nop 0
	v_add_f32_e32 v2, v2, v3
	v_fmamk_f32 v2, v2, 0x3a800000, v162
	v_mul_f32_e32 v3, 0x4b800000, v2
	v_cmp_gt_f32_e32 vcc, s69, v2
	s_nop 1
	v_cndmask_b32_e32 v2, v2, v3, vcc
	v_rsq_f32_e32 v2, v2
	s_nop 0
	v_mul_f32_e32 v3, 0x45800000, v2
	v_cndmask_b32_e32 v2, v2, v3, vcc
	v_mul_f32_e32 v0, v0, v2
	v_mul_f32_e32 v3, v21, v2
	v_cvt_pk_bf16_f32 v0, v0, v3
	v_mul_f32_e32 v4, v22, v2
	v_mul_f32_e32 v2, v20, v2
	flat_store_dword v[60:61], v0
	v_cvt_pk_bf16_f32 v0, v4, v2
	flat_store_dword v[60:61], v0 offset:64
	s_waitcnt lgkmcnt(0)
	s_barrier
	s_cbranch_scc1 .LBB0_586

; #define LAS __attribute__((address_space(3)))
; template <int MODE>
; __device__ __forceinline__ void sgemm_phase(LAS unsigned char* lds, const SgArgs g, int ntiles, int bid, int G) {
;     ...
;     for (int t = bid; t < ntiles; t += G) {
;         const int ct = t >> 3, rt = t & 7;
;         const int brow0 = MODE == 0 ? 256 * (ct >> 2) + 32 * (ct & 3) : 64 * ct, brow1 = MODE == 0 ? brow0 + 128 : brow0 + 32;
;         const bf16_t* ap = g.A + (size_t)(MP + rt * 32 + r32) * g.lda + wave * kw + hi * 8;
;         const bf16_t* bp0 = g.Bt + (size_t)(brow0 + r32) * g.ldb + wave * kw + hi * 8;
;         const bf16_t* bp1 = g.Bt + (size_t)(brow1 + r32) * g.ldb + wave * kw + hi * 8;
;         f32x16 c0 = {}, c1 = {};
;         for (int k0 = 0; k0 < kw; k0 += 128) {
;             bf16x8 a[8], b0[8], b1[8];
; #pragma unroll
;             for (int i = 0; i < 8; ++i) if (k0 + 16 * i < kw) { a[i] = *(const bf16x8*)(ap + k0 + 16 * i); b0[i] = *(const bf16x8*)(bp0 + k0 + 16 * i); b1[i] = *(const bf16x8*)(bp1 + k0 + 16 * i); }
;             asm volatile("" ::: "memory");
; #pragma unroll
;             for (int i = 0; i < 8; ++i) if (k0 + 16 * i < kw) { c0 = __builtin_amdgcn_mfma_f32_32x32x16_bf16(a[i], b0[i], c0, 0, 0, 0); c1 = __builtin_amdgcn_mfma_f32_32x32x16_bf16(a[i], b1[i], c1, 0, 0, 0); }
;         }
;         LAS float* red = (LAS float*)lds + wave * 2048;
; #pragma unroll
;         for (int r = 0; r < 16; ++r) { const int row = (r & 3) + 8 * (r >> 2) + 4 * hi; red[row * 64 + r32] = c0[r]; red[row * 64 + 32 + r32] = c1[r]; }
;         __syncthreads();
.LBB0_592:
	s_and_b32 s1, s5, 0xe0
	s_and_b32 s0, s4, 0xffffffc0
	s_bitset1_b32 s1, 15
	v_or_b32_e32 v2, s0, v40
	v_or_b32_e32 v0, s1, v40
	v_ashrrev_i32_e32 v3, 31, v2
	v_or_b32_e32 v4, 32, v2
	v_lshlrev_b32_e32 v0, 11, v0
	v_lshlrev_b64 v[2:3], 11, v[2:3]
	v_ashrrev_i32_e32 v5, 31, v4
	v_lshl_add_u64 v[56:57], v[34:35], 0, v[0:1]
	v_lshl_add_u64 v[58:59], v[36:37], 0, v[2:3]
	v_lshlrev_b64 v[6:7], 11, v[4:5]
	v_lshl_add_u64 v[60:61], v[36:37], 0, v[6:7]
	global_load_dwordx4 v[190:193], v[56:57], off
	global_load_dwordx4 v[222:225], v[58:59], off
	global_load_dwordx4 v[132:135], v[60:61], off
	global_load_dwordx4 v[194:197], v[56:57], off offset:32
	global_load_dwordx4 v[226:229], v[58:59], off offset:32
	global_load_dwordx4 v[136:139], v[60:61], off offset:32
	global_load_dwordx4 v[198:201], v[56:57], off offset:64
	global_load_dwordx4 v[230:233], v[58:59], off offset:64
	global_load_dwordx4 v[140:143], v[60:61], off offset:64
	global_load_dwordx4 v[202:205], v[56:57], off offset:96
	global_load_dwordx4 v[234:237], v[58:59], off offset:96
	global_load_dwordx4 v[144:147], v[60:61], off offset:96
	global_load_dwordx4 v[206:209], v[56:57], off offset:128
	global_load_dwordx4 v[238:241], v[58:59], off offset:128
	global_load_dwordx4 v[148:151], v[60:61], off offset:128
	global_load_dwordx4 v[210:213], v[56:57], off offset:160
	global_load_dwordx4 v[242:245], v[58:59], off offset:160
	global_load_dwordx4 v[152:155], v[60:61], off offset:160
	global_load_dwordx4 v[214:217], v[56:57], off offset:192
	global_load_dwordx4 v[246:249], v[58:59], off offset:192
	global_load_dwordx4 v[156:159], v[60:61], off offset:192
	global_load_dwordx4 v[218:221], v[56:57], off offset:224
	global_load_dwordx4 v[250:253], v[58:59], off offset:224
	global_load_dwordx4 v[164:167], v[60:61], off offset:224
	v_add_u32_e32 v0, 0x800, v41
	v_add_u32_e32 v39, 0x1000, v41
	s_add_i32 s6, s6, s86
	s_add_i32 s5, s5, s87
	s_add_i32 s4, s4, s2
	v_add_u32_e32 v56, 0x1800, v41
	v_add_u32_e32 v57, 0x2000, v43
	v_add_u32_e32 v52, s1, v42
	v_ashrrev_i32_e32 v53, 31, v52
	v_lshlrev_b64 v[54:55], 6, v[52:53]
	v_lshl_add_u64 v[54:55], s[12:13], 0, v[54:55]
	s_ashr_i32 s1, s0, 31
	s_cmpk_gt_i32 s6, 0x7f
	s_waitcnt vmcnt(21)
	v_mfma_f32_32x32x16_bf16 v[2:17], v[190:193], v[222:225], 0
	v_mfma_f32_32x32x16_bf16 v[18:33], v[190:193], v[132:135], 0
	s_waitcnt vmcnt(18)
	v_mfma_f32_32x32x16_bf16 v[2:17], v[194:197], v[226:229], v[2:17]
	v_mfma_f32_32x32x16_bf16 v[18:33], v[194:197], v[136:139], v[18:33]
	s_waitcnt vmcnt(15)
	v_mfma_f32_32x32x16_bf16 v[2:17], v[198:201], v[230:233], v[2:17]
	v_mfma_f32_32x32x16_bf16 v[18:33], v[198:201], v[140:143], v[18:33]
	s_waitcnt vmcnt(12)
	v_mfma_f32_32x32x16_bf16 v[2:17], v[202:205], v[234:237], v[2:17]
	v_mfma_f32_32x32x16_bf16 v[18:33], v[202:205], v[144:147], v[18:33]
	s_waitcnt vmcnt(9)
	v_mfma_f32_32x32x16_bf16 v[2:17], v[206:209], v[238:241], v[2:17]
	v_mfma_f32_32x32x16_bf16 v[18:33], v[206:209], v[148:151], v[18:33]
	s_waitcnt vmcnt(6)
	v_mfma_f32_32x32x16_bf16 v[2:17], v[210:213], v[242:245], v[2:17]
	v_mfma_f32_32x32x16_bf16 v[18:33], v[210:213], v[152:155], v[18:33]
	s_waitcnt vmcnt(3)
	v_mfma_f32_32x32x16_bf16 v[2:17], v[214:217], v[246:249], v[2:17]
	v_mfma_f32_32x32x16_bf16 v[18:33], v[214:217], v[156:159], v[18:33]
	s_waitcnt vmcnt(0)
	v_mfma_f32_32x32x16_bf16 v[2:17], v[218:221], v[250:253], v[2:17]
	v_mfma_f32_32x32x16_bf16 v[18:33], v[218:221], v[164:167], v[18:33]
	s_nop 11
	ds_write2_b32 v41, v2, v18 offset1:32
	ds_write2_b32 v41, v3, v19 offset0:64 offset1:96
	ds_write2_b32 v41, v4, v20 offset0:128 offset1:160
	ds_write2_b32 v41, v5, v21 offset0:192 offset1:224
	ds_write2_b32 v0, v6, v22 offset1:32
	ds_write2_b32 v0, v7, v23 offset0:64 offset1:96
	ds_write2_b32 v0, v8, v24 offset0:128 offset1:160
	ds_write2_b32 v0, v9, v25 offset0:192 offset1:224
	ds_write2_b32 v39, v10, v26 offset1:32
	ds_write2_b32 v39, v11, v27 offset0:64 offset1:96
	ds_write2_b32 v39, v12, v28 offset0:128 offset1:160
	ds_write2_b32 v39, v13, v29 offset0:192 offset1:224
	ds_write2_b32 v56, v14, v30 offset1:32
	ds_write2_b32 v56, v15, v31 offset0:64 offset1:96
	ds_write2_b32 v56, v16, v32 offset0:128 offset1:160
	ds_write2_b32 v56, v17, v33 offset0:192 offset1:224
	s_waitcnt lgkmcnt(0)
	s_barrier
; #define LAS __attribute__((address_space(3)))
; __device__ __forceinline__ unsigned cvt_pk_bf16(float lo, float hi) { unsigned r; asm volatile("v_cvt_pk_bf16_f32 %0, %1, %2" : "=v"(r) : "v"(lo), "v"(hi)); return r; }
; __device__ __forceinline__ float row_rstd(const float* ssq, int row) {
;     const f32x4* p = (const f32x4*)(ssq + (size_t)row * 16);
;     const f32x4 a = p[0], b = p[1], c = p[2], d = p[3];
;     const float s = (((a.x + a.y) + (a.z + a.w)) + ((b.x + b.y) + (b.z + b.w))) + (((c.x + c.y) + (c.z + c.w)) + ((d.x + d.y) + (d.z + d.w)));
;     return rsqrtf(s * (1.0f / 1024.0f) + EPS);
; template <int MODE>
; __device__ __forceinline__ void sgemm_phase(LAS unsigned char* lds, const SgArgs g, int ntiles, int bid, int G) {
;     ...
;         const int row = tid >> 4, q = tid & 15; float v0 = 0.f, v1 = 0.f, v2 = 0.f, v3 = 0.f;
; #pragma unroll
;         for (int w = 0; w < 8; ++w) { const LAS float* p = (const LAS float*)lds + w * 2048 + row * 64 + 2 * q; const f32x2 lo = *(const LAS f32x2*)p, hi2 = *(const LAS f32x2*)(p + 32); v0 += lo.x; v1 += lo.y; v2 += hi2.x; v3 += hi2.y; }
;         const int grow = MP + rt * 32 + row;
;         if (MODE == 0) {
;             const float rs = row_rstd(g.ssq_in, grow); const float g0 = v0 * rs, g1 = v1 * rs, u0 = v2 * rs, u1 = v3 * rs;
;             const float a0 = g0 * __builtin_amdgcn_rcpf(1.0f + __builtin_amdgcn_exp2f(-1.4426950408889634f * g0)) * u0, a1 = g1 * __builtin_amdgcn_rcpf(1.0f + __builtin_amdgcn_exp2f(-1.4426950408889634f * g1)) * u1;
;             *(unsigned*)(g.O + (size_t)grow * g.ldc + 128 * (ct >> 2) + 32 * (ct & 3) + 2 * q) = cvt_pk_bf16(a0, a1);
;         } else if (MODE == 1) {
;             const float rs = row_rstd(g.ssq_in, grow); bf16_t* op = g.O + (size_t)grow * g.ldc + 64 * ct + 2 * q;
;             *(unsigned*)op = cvt_pk_bf16(v0 * rs, v1 * rs); *(unsigned*)(op + 32) = cvt_pk_bf16(v2 * rs, v3 * rs);
	flat_load_dwordx4 v[2:5], v[54:55]
	flat_load_dwordx4 v[6:9], v[54:55] offset:32
	flat_load_dwordx4 v[10:13], v[54:55] offset:16
	flat_load_dwordx4 v[14:17], v[54:55] offset:48
	v_lshlrev_b64 v[18:19], 11, v[52:53]
	v_lshl_add_u64 v[18:19], s[16:17], 0, v[18:19]
	v_add_u32_e32 v30, 0x6000, v43
	v_add_u32_e32 v44, 0x8000, v43
	v_add_u32_e32 v48, 0xa000, v43
	v_add_u32_e32 v54, 0xc000, v43
	v_add_u32_e32 v56, 0xe000, v43
	v_mov_b32_e32 v39, v1
	v_lshl_add_u64 v[18:19], s[0:1], 1, v[18:19]
	v_add_u32_e32 v0, 0x4000, v43
	v_lshl_add_u64 v[60:61], v[18:19], 0, v[38:39]
	ds_read2_b64 v[18:21], v43 offset1:16
	ds_read2_b64 v[22:25], v57 offset1:16
	ds_read2_b64 v[26:29], v0 offset1:16
	ds_read2_b64 v[30:33], v30 offset1:16
	ds_read2_b64 v[44:47], v44 offset1:16
	ds_read2_b64 v[48:51], v48 offset1:16
	ds_read2_b64 v[52:55], v54 offset1:16
	ds_read2_b64 v[56:59], v56 offset1:16
	s_waitcnt lgkmcnt(0)
	v_add_f32_e32 v0, 0, v18
	v_add_f32_e32 v18, 0, v19
	v_add_f32_e32 v19, 0, v20
	v_add_f32_e32 v18, v18, v23
	v_add_f32_e32 v19, v19, v24
	v_add_f32_e32 v18, v18, v27
	v_add_f32_e32 v19, v19, v28
	v_add_f32_e32 v18, v18, v31
	v_add_f32_e32 v19, v19, v32
	v_add_f32_e32 v18, v18, v45
	v_add_f32_e32 v19, v19, v46
	v_add_f32_e32 v18, v18, v49
	v_add_f32_e32 v19, v19, v50
	v_add_f32_e32 v18, v18, v53
	v_add_f32_e32 v19, v19, v54
	v_add_f32_e32 v20, 0, v21
	v_add_f32_e32 v0, v0, v22
	v_add_f32_e32 v21, v18, v57
	v_add_f32_e32 v22, v19, v58
	v_add_f32_e32 v20, v20, v25
	v_add_f32_e32 v0, v0, v26
	v_add_f32_e32 v20, v20, v29
	v_add_f32_e32 v0, v0, v30
	v_add_f32_e32 v20, v20, v33
	v_add_f32_e32 v0, v0, v44
	v_add_f32_e32 v20, v20, v47
	v_add_f32_e32 v0, v0, v48
	v_add_f32_e32 v20, v20, v51
	v_add_f32_e32 v0, v0, v52
	v_add_f32_e32 v20, v20, v55
	v_add_f32_e32 v0, v0, v56
	v_add_f32_e32 v20, v20, v59
	s_waitcnt vmcnt(0)
	v_mov_b32_e32 v18, v2
	v_mov_b32_e32 v19, v6
	v_mov_b32_e32 v6, v3
	v_mov_b32_e32 v2, v4
	v_mov_b32_e32 v3, v8
	v_mov_b32_e32 v8, v5
	v_mov_b32_e32 v4, v10
	v_mov_b32_e32 v5, v14
	v_mov_b32_e32 v14, v11
	v_mov_b32_e32 v10, v12
	v_mov_b32_e32 v11, v16
	v_mov_b32_e32 v16, v13
	v_pk_add_f32 v[6:7], v[18:19], v[6:7]
	v_pk_add_f32 v[2:3], v[2:3], v[8:9]
	v_pk_add_f32 v[4:5], v[4:5], v[14:15]
	v_pk_add_f32 v[8:9], v[10:11], v[16:17]
	v_pk_add_f32 v[2:3], v[6:7], v[2:3]
	v_pk_add_f32 v[4:5], v[4:5], v[8:9]
	s_nop 0
	v_pk_add_f32 v[2:3], v[2:3], v[4:5]
	s_nop 0
	v_add_f32_e32 v2, v2, v3
	v_fmamk_f32 v2, v2, 0x3a800000, v162
	v_mul_f32_e32 v3, 0x4b800000, v2
	v_cmp_gt_f32_e32 vcc, s69, v2
	s_nop 1
	v_cndmask_b32_e32 v2, v2, v3, vcc
	v_rsq_f32_e32 v2, v2
	s_nop 0
	v_mul_f32_e32 v3, 0x45800000, v2
	v_cndmask_b32_e32 v2, v2, v3, vcc
	v_mul_f32_e32 v0, v0, v2
	v_mul_f32_e32 v3, v21, v2
	v_mul_f32_e32 v4, v22, v2
	v_mul_f32_e32 v2, v20, v2
	v_cvt_pk_bf16_f32 v0, v0, v3
	flat_store_dword v[60:61], v0
	v_cvt_pk_bf16_f32 v0, v4, v2
	flat_store_dword v[60:61], v0 offset:64
	s_waitcnt lgkmcnt(0)
	s_barrier
	s_cbranch_scc0 .LBB0_592
